# final RMS norm loop: all loads of a row requested together with counted waits (was one memory round trip per 16-byte column chunk)
# speedup vs baseline: 1.0093x; 1.0048x over previous
.LBB0_1754:
	s_movk_i32 s8, 0xe0
	global_load_dwordx4 v[8:11], v[4:5], off offset:-32
	global_load_dwordx4 v[12:15], v[4:5], off
	global_load_dwordx4 v[16:19], v[4:5], off offset:-16
	global_load_dwordx4 v[20:23], v[4:5], off offset:16
	s_load_dwordx2 s[8:9], s[90:91], s8 offset:0x0
	v_add_u32_e32 v0, s10, v0
	v_lshl_add_u64 v[4:5], v[4:5], 0, s[4:5]
	s_waitcnt lgkmcnt(0)
	global_load_dwordx4 v[24:27], v1, s[8:9]
	global_load_dwordx4 v[28:31], v[2:3], off offset:-2048
	global_load_dwordx4 v[32:35], v[2:3], off offset:-1024
	global_load_dwordx4 v[40:43], v1, s[8:9] offset:1024
	global_load_dwordx4 v[44:47], v1, s[8:9] offset:2048
	global_load_dwordx4 v[48:51], v1, s[8:9] offset:3072
	global_load_dwordx4 v[52:55], v[2:3], off
	global_load_dwordx4 v[56:59], v[2:3], off offset:1024
	s_waitcnt vmcnt(11)
	v_mov_b32_e32 v36, v8
	s_waitcnt vmcnt(10)
	v_mov_b32_e32 v37, v12
	v_mov_b32_e32 v12, v9
	v_mov_b32_e32 v8, v10
	v_mov_b32_e32 v9, v14
	v_mov_b32_e32 v14, v11
	s_waitcnt vmcnt(9)
	v_mov_b32_e32 v10, v16
	s_waitcnt vmcnt(8)
	v_mov_b32_e32 v11, v20
	v_mov_b32_e32 v20, v17
	v_mov_b32_e32 v16, v18
	v_mov_b32_e32 v17, v22
	v_mov_b32_e32 v22, v19
	v_pk_add_f32 v[12:13], v[36:37], v[12:13]
	v_pk_add_f32 v[8:9], v[8:9], v[14:15]
	v_pk_add_f32 v[10:11], v[10:11], v[20:21]
	v_pk_add_f32 v[14:15], v[16:17], v[22:23]
	v_pk_add_f32 v[8:9], v[12:13], v[8:9]
	v_pk_add_f32 v[10:11], v[10:11], v[14:15]
	s_nop 0
	v_pk_add_f32 v[8:9], v[8:9], v[10:11]
	s_nop 0
	v_add_f32_e32 v7, v8, v9
	v_fmamk_f32 v7, v7, 0x3a800000, v6
	v_mul_f32_e32 v8, 0x4b800000, v7
	v_cmp_gt_f32_e32 vcc, s0, v7
	s_nop 1
	v_cndmask_b32_e32 v7, v7, v8, vcc
	v_rsq_f32_e32 v7, v7
	s_nop 0
	v_mul_f32_e32 v8, 0x45800000, v7
	v_cndmask_b32_e32 v20, v7, v8, vcc
	s_waitcnt vmcnt(7)
	v_pk_mul_f32 v[8:9], v[20:21], v[24:25] op_sel_hi:[0,1]
	v_pk_mul_f32 v[10:11], v[20:21], v[26:27] op_sel_hi:[0,1]
	s_waitcnt vmcnt(6)
	v_pk_mul_f32 v[8:9], v[28:29], v[8:9]
	v_pk_mul_f32 v[10:11], v[30:31], v[10:11]
	global_store_dwordx4 v[2:3], v[8:11], off offset:-2048
	v_cmp_lt_i32_e32 vcc, s1, v0
	s_or_b64 s[6:7], vcc, s[6:7]
	s_waitcnt vmcnt(5)
	v_pk_mul_f32 v[12:13], v[20:21], v[40:41] op_sel_hi:[0,1]
	v_pk_mul_f32 v[14:15], v[20:21], v[42:43] op_sel_hi:[0,1]
	v_pk_mul_f32 v[12:13], v[32:33], v[12:13]
	v_pk_mul_f32 v[14:15], v[34:35], v[14:15]
	global_store_dwordx4 v[2:3], v[12:15], off offset:-1024
	s_waitcnt vmcnt(3)
	v_pk_mul_f32 v[16:17], v[20:21], v[44:45] op_sel_hi:[0,1]
	v_pk_mul_f32 v[18:19], v[20:21], v[46:47] op_sel_hi:[0,1]
	s_nop 0
	v_pk_mul_f32 v[16:17], v[52:53], v[16:17]
	v_pk_mul_f32 v[18:19], v[54:55], v[18:19]
	global_store_dwordx4 v[2:3], v[16:19], off
	s_waitcnt vmcnt(3)
	v_pk_mul_f32 v[8:9], v[20:21], v[48:49] op_sel_hi:[0,1]
	v_pk_mul_f32 v[10:11], v[20:21], v[50:51] op_sel_hi:[0,1]
	s_nop 0
	v_pk_mul_f32 v[8:9], v[56:57], v[8:9]
	v_pk_mul_f32 v[10:11], v[58:59], v[10:11]
	global_store_dwordx4 v[2:3], v[8:11], off offset:1024
	v_lshl_add_u64 v[2:3], v[2:3], 0, s[2:3]
	s_andn2_b64 exec, exec, s[6:7]
	s_cbranch_execnz .LBB0_1754
